# speedup vs baseline: 1.1155x; 1.0082x over previous
; DEV int otid() { int t = threadIdx.x; asm volatile("" : "+v"(t)); return t; }
; template <bool SWAP, class RowA, class Epi>
; DEV void gemm_tile(unsigned char* smem, RowA rowA, const bf16_t* Bt, int K, Epi epi) {
;   const int tid = otid(), lane = tid & 63, wid = tid >> 6, wr = wid >> 1, wc = wid & 1, fr = lane & 15, fq = lane >> 4;
;   const int r0 = tid >> 2;
;   const int a_w = (r0 >> 2) & 3, g_w = (((a_w ^ (a_w >> 1)) & 1) << 1) | (a_w >> 1);
;   const int cc = ((tid & 3) ^ g_w) * 8;
;   const int a_r = (fr >> 2) & 3, g_r = (((a_r ^ (a_r >> 1)) & 1) << 1) | (a_r >> 1);
;   const int rdoff = fr * 64 + ((fq ^ g_r) * 16);
;   const bf16_t* a0 = rowA(r0) + cc;
;   const bf16_t* a1 = rowA(r0 + 64) + cc;
;   const bf16_t* b0 = Bt + (size_t)r0 * K + cc;
;   const bf16_t* b1 = Bt + (size_t)(r0 + 64) * K + cc;
;   f32x4 acc[4][4];
; #pragma unroll
;   for (int m = 0; m < 4; ++m)
; #pragma unroll
;     for (int n = 0; n < 4; ++n) acc[m][n] = f32x4{0.f, 0.f, 0.f, 0.f};
; DEV void phase_qkv(const Params& p, unsigned char* smem) {
;     ...
;   for (int t = blockIdx.x; t < ntile; t += gridDim.x) {
;     int nt = t % 12, mt = t / 12;
;     const bf16_t* A = p.hbuf + (size_t)mt * 128 * 1024;
;     if (nt < 10) {
;       gemm_tile<true>(smem, [&](int r) { return A + (size_t)r * 1024; }, p.wqkv_t + (size_t)nt * 128 * 1024, 1024,
.LBB0_174:
	s_and_b32 s0, s8, 7
	s_mul_i32 s0, s0, 0xc6
	s_lshr_b32 s1, s8, 3
	s_add_i32 s34, s0, s1
	s_mul_hi_i32 s0, s34, 0x2aaaaaab
	s_lshr_b32 s1, s0, 31
	s_ashr_i32 s0, s0, 1
	s_add_i32 s0, s0, s1
	s_mul_i32 s1, s0, 12
	s_sub_i32 s34, s34, s1
	s_ashr_i32 s1, s0, 31
	v_readlane_b32 s44, v165, 23
	s_lshl_b64 s[36:37], s[0:1], 18
	v_readlane_b32 s54, v165, 33
	v_readlane_b32 s55, v165, 34
	v_readlane_b32 s56, v165, 35
	v_readlane_b32 s57, v165, 36
	v_readlane_b32 s58, v165, 37
	v_readlane_b32 s59, v165, 38
	s_add_u32 s36, s54, s36
	v_readlane_b32 s56, v165, 39
	s_addc_u32 s37, s55, s37
	v_readlane_b32 s57, v165, 40
	v_readlane_b32 s58, v165, 41
	v_readlane_b32 s59, v165, 42
	v_readlane_b32 s60, v165, 43
	v_readlane_b32 s61, v165, 44
	v_readlane_b32 s62, v165, 45
	v_readlane_b32 s63, v165, 46
	v_readlane_b32 s64, v165, 47
	v_readlane_b32 s65, v165, 48
	v_readlane_b32 s66, v165, 49
	v_readlane_b32 s67, v165, 50
	v_readlane_b32 s68, v165, 51
	v_readlane_b32 s69, v165, 52
	v_readlane_b32 s70, v165, 53
	v_readlane_b32 s71, v165, 54
	s_cmp_gt_i32 s34, 9
	s_mov_b64 s[38:39], -1
	v_readlane_b32 s45, v165, 24
	v_readlane_b32 s46, v165, 25
	v_readlane_b32 s47, v165, 26
	v_readlane_b32 s48, v165, 27
	v_readlane_b32 s49, v165, 28
	v_readlane_b32 s50, v165, 29
	v_readlane_b32 s51, v165, 30
	v_readlane_b32 s52, v165, 31
	v_readlane_b32 s53, v165, 32
	s_cbranch_scc0 .LBB0_194
	v_mov_b32_e32 v8, v122
	s_mov_b32 s35, s9
	v_lshrrev_b32_e32 v1, 4, v8
	v_lshrrev_b32_e32 v2, 5, v8
	v_xor_b32_e32 v1, v1, v2
	v_lshlrev_b32_e32 v1, 1, v1
	v_readlane_b32 s72, v165, 7
	v_ashrrev_i32_e32 v0, 2, v8
	v_bfe_u32 v3, v8, 5, 1
	v_and_b32_e32 v1, 2, v1
	v_and_b32_e32 v2, 3, v8
	s_lshl_b64 s[38:39], s[34:35], 18
	v_readlane_b32 s80, v165, 15
	v_bitop3_b32 v9, v1, v2, v3 bitop3:0x36
	v_ashrrev_i32_e32 v1, 31, v0
	v_readlane_b32 s81, v165, 16
	s_add_u32 s38, s80, s38
	v_lshlrev_b64 v[0:1], 11, v[0:1]
	s_addc_u32 s39, s81, s39
	v_lshl_add_u64 v[2:3], v[0:1], 0, s[22:23]
	v_lshl_add_u64 v[4:5], s[36:37], 0, v[2:3]
	v_lshl_add_u64 v[6:7], s[38:39], 0, v[0:1]
	v_lshl_add_u64 v[0:1], s[36:37], 0, v[0:1]
	v_lshlrev_b32_e32 v80, 4, v9
	v_lshlrev_b32_e32 v68, 4, v8
	v_lshl_add_u64 v[64:65], v[0:1], 0, v[80:81]
	v_lshl_add_u64 v[0:1], v[4:5], 0, v[80:81]
	v_readfirstlane_b32 s1, v68
	v_add_u32_e32 v5, 0x1000, v68
	s_mov_b32 m0, s1
	v_readfirstlane_b32 s1, v5
	v_add_u32_e32 v4, 0x2000, v68
	s_mov_b32 m0, s1
	v_readfirstlane_b32 s1, v4
	v_add_u32_e32 v0, 0x3000, v68
	v_lshl_add_u64 v[2:3], s[38:39], 0, v[2:3]
	v_lshl_add_u64 v[66:67], v[6:7], 0, v[80:81]
	s_mov_b32 m0, s1
	v_readfirstlane_b32 s1, v0
	v_lshl_add_u64 v[2:3], v[2:3], 0, v[80:81]
	s_mov_b32 m0, s1
	v_lshrrev_b32_e32 v0, 2, v8
	v_lshrrev_b32_e32 v1, 3, v8
	v_xor_b32_e32 v0, v0, v1
	v_lshlrev_b32_e32 v0, 1, v0
	v_bfe_u32 v85, v8, 4, 2
	v_bfe_u32 v2, v8, 3, 1
	v_and_b32_e32 v0, 2, v0
	v_and_b32_e32 v95, 15, v8
	v_bitop3_b32 v0, v0, v85, v2 bitop3:0x36
	v_lshlrev_b32_e32 v1, 6, v95
	v_bfe_u32 v82, v8, 6, 1
	v_ashrrev_i32_e32 v83, 7, v8
	v_lshl_or_b32 v69, v0, 4, v1
	v_mov_b32_e32 v0, 0
	v_lshlrev_b32_e32 v71, 12, v83
	v_lshlrev_b32_e32 v70, 12, v82
	s_mov_b32 s1, 0
	s_mov_b64 s[38:39], 0
	v_mov_b32_e32 v1, v0
	v_mov_b32_e32 v2, v0
	v_mov_b32_e32 v3, v0
	v_mov_b32_e32 v4, v0
	v_mov_b32_e32 v5, v0
	v_mov_b32_e32 v6, v0
	v_mov_b32_e32 v7, v0
	v_mov_b32_e32 v8, v0
	v_mov_b32_e32 v9, v0
	v_mov_b32_e32 v10, v0
	v_mov_b32_e32 v11, v0
	v_mov_b32_e32 v12, v0
	v_mov_b32_e32 v13, v0
	v_mov_b32_e32 v14, v0
	v_mov_b32_e32 v15, v0
	v_mov_b32_e32 v16, v0
	v_mov_b32_e32 v17, v0
	v_mov_b32_e32 v18, v0
	v_mov_b32_e32 v19, v0
	v_mov_b32_e32 v20, v0
	v_mov_b32_e32 v21, v0
	v_mov_b32_e32 v22, v0
	v_mov_b32_e32 v23, v0
	v_mov_b32_e32 v24, v0
	v_mov_b32_e32 v25, v0
	v_mov_b32_e32 v26, v0
	v_mov_b32_e32 v27, v0
	v_mov_b32_e32 v28, v0
	v_mov_b32_e32 v29, v0
	v_mov_b32_e32 v30, v0
	v_mov_b32_e32 v31, v0
	v_mov_b32_e32 v32, v0
	v_mov_b32_e32 v33, v0
	v_mov_b32_e32 v34, v0
	v_mov_b32_e32 v35, v0
	v_mov_b32_e32 v36, v0
	v_mov_b32_e32 v37, v0
	v_mov_b32_e32 v38, v0
	v_mov_b32_e32 v39, v0
	v_mov_b32_e32 v40, v0
	v_mov_b32_e32 v41, v0
	v_mov_b32_e32 v42, v0
	v_mov_b32_e32 v43, v0
	v_mov_b32_e32 v44, v0
	v_mov_b32_e32 v45, v0
	v_mov_b32_e32 v46, v0
	v_mov_b32_e32 v47, v0
	v_mov_b32_e32 v48, v0
	v_mov_b32_e32 v49, v0
	v_mov_b32_e32 v50, v0
	v_mov_b32_e32 v51, v0
	v_mov_b32_e32 v52, v0
	v_mov_b32_e32 v53, v0
	v_mov_b32_e32 v54, v0
	v_mov_b32_e32 v55, v0
	v_mov_b32_e32 v56, v0
	v_mov_b32_e32 v57, v0
	v_mov_b32_e32 v58, v0
	v_mov_b32_e32 v59, v0
	v_mov_b32_e32 v60, v0
	v_mov_b32_e32 v61, v0
	v_mov_b32_e32 v62, v0
	v_mov_b32_e32 v63, v0
	v_readlane_b32 s73, v165, 8
	v_readlane_b32 s74, v165, 9
	v_readlane_b32 s75, v165, 10
	v_readlane_b32 s76, v165, 11
	v_readlane_b32 s77, v165, 12
	v_readlane_b32 s78, v165, 13
	v_readlane_b32 s79, v165, 14
	v_readlane_b32 s82, v165, 17
	v_readlane_b32 s83, v165, 18
	v_readlane_b32 s84, v165, 19
	v_readlane_b32 s85, v165, 20
	v_readlane_b32 s86, v165, 21
	v_readlane_b32 s87, v165, 22
	v_and_b32_e32 v72, 15, v122
	v_bfe_u32 v73, v122, 4, 2
	v_bfe_u32 v74, v122, 1, 3
	v_xor_b32_e32 v73, v73, v74
	v_lshlrev_b32_e32 v73, 4, v73
	v_lshl_or_b32 v69, v72, 7, v73
	v_lshlrev_b32_e32 v71, 1, v71
	v_lshlrev_b32_e32 v70, 1, v70
	v_and_b32_e32 v72, 7, v122
	v_bfe_u32 v73, v122, 4, 3
	v_xor_b32_e32 v72, v72, v73
	v_lshlrev_b32_e32 v72, 4, v72
	v_lshrrev_b32_e32 v73, 3, v122
	v_lshl_or_b32 v72, v73, 11, v72
	v_bfe_u32 v73, v122, 4, 2
	v_lshrrev_b32_e32 v74, 1, v73
	v_xor_b32_e32 v75, v73, v74
	v_and_b32_e32 v75, 1, v75
	v_lshl_or_b32 v74, v75, 1, v74
	v_and_b32_e32 v73, 3, v122
	v_xor_b32_e32 v73, v73, v74
	v_lshlrev_b32_e32 v73, 4, v73
	v_lshrrev_b32_e32 v74, 2, v122
	v_lshl_or_b32 v73, v74, 11, v73
	v_sub_u32_e32 v72, v72, v73
	v_ashrrev_i32_e32 v73, 31, v72
	v_lshl_add_u64 v[64:65], v[64:65], 0, v[72:73]
	v_lshl_add_u64 v[66:67], v[66:67], 0, v[72:73]
	v_mov_b32_e32 v144, 0x10000
	v_mov_b32_e32 v145, 0

; DEV int otid() { int t = threadIdx.x; asm volatile("" : "+v"(t)); return t; }
; template <bool SWAP, class RowA, class Epi>
; DEV void gemm_tile(unsigned char* smem, RowA rowA, const bf16_t* Bt, int K, Epi epi) {
;   const int tid = otid(), lane = tid & 63, wid = tid >> 6, wr = wid >> 1, wc = wid & 1, fr = lane & 15, fq = lane >> 4;
;   const int r0 = tid >> 2;
;   const int a_w = (r0 >> 2) & 3, g_w = (((a_w ^ (a_w >> 1)) & 1) << 1) | (a_w >> 1);
;   const int cc = ((tid & 3) ^ g_w) * 8;
;   const int a_r = (fr >> 2) & 3, g_r = (((a_r ^ (a_r >> 1)) & 1) << 1) | (a_r >> 1);
;   const int rdoff = fr * 64 + ((fq ^ g_r) * 16);
;   const bf16_t* a0 = rowA(r0) + cc;
;   const bf16_t* a1 = rowA(r0 + 64) + cc;
;   const bf16_t* b0 = Bt + (size_t)r0 * K + cc;
;   const bf16_t* b1 = Bt + (size_t)(r0 + 64) * K + cc;
;   f32x4 acc[4][4];
; #pragma unroll
;   for (int m = 0; m < 4; ++m)
; #pragma unroll
;     for (int n = 0; n < 4; ++n) acc[m][n] = f32x4{0.f, 0.f, 0.f, 0.f};
; DEV void phase_proj_out(const Params& p, const bf16_t* Abuf, const bf16_t* Wt, const float* bias, int nrows, unsigned char* smem, bool drain) {
;     ...
;   for (int t = blockIdx.x; t < ntile; t += gridDim.x) {
;     int nt = t & 7, mt = t >> 3;
;     const bf16_t* A = Abuf + (size_t)mt * 128 * 1024;
;     gemm_tile<true>(smem, [&](int r) { return A + (size_t)r * 1024; }, Wt + (size_t)nt * 128 * 1024, 1024,
.LBB0_342:
	v_mov_b32_e32 v10, v122
	s_and_b32 s0, s19, 7
	s_mul_i32 s0, s0, 0x84
	s_lshr_b32 s16, s19, 3
	s_add_i32 s0, s0, s16
	s_and_b32 s23, s0, 7
	s_ashr_i32 s16, s0, 3
	v_lshrrev_b32_e32 v1, 4, v10
	v_lshrrev_b32_e32 v2, 5, v10
	v_xor_b32_e32 v1, v1, v2
	s_mov_b32 s0, s23
	s_ashr_i32 s17, s16, 31
	v_lshlrev_b32_e32 v1, 1, v1
	s_lshl_b32 s8, s0, 18
	s_lshl_b64 s[0:1], s[16:17], 18
	v_ashrrev_i32_e32 v0, 2, v10
	v_bfe_u32 v3, v10, 5, 1
	v_and_b32_e32 v1, 2, v1
	v_and_b32_e32 v2, 3, v10
	s_add_u32 s0, s60, s0
	v_bitop3_b32 v11, v1, v2, v3 bitop3:0x36
	v_ashrrev_i32_e32 v1, 31, v0
	s_addc_u32 s1, s61, s1
	v_lshlrev_b64 v[0:1], 11, v[0:1]
	v_readlane_b32 s72, v165, 7
	v_lshl_add_u64 v[2:3], v[0:1], 0, s[30:31]
	v_lshl_add_u64 v[8:9], s[0:1], 0, v[0:1]
	v_lshlrev_b32_e32 v72, 4, v11
	v_lshlrev_b32_e32 v70, 4, v10
	s_lshl_b32 s17, s23, 18
	v_readlane_b32 s82, v165, 17
	v_lshl_add_u64 v[4:5], s[0:1], 0, v[2:3]
	v_lshl_add_u64 v[64:65], v[8:9], 0, v[72:73]
	v_readfirstlane_b32 s0, v70
	v_add_u32_e32 v9, 0x1000, v70
	v_readlane_b32 s83, v165, 18
	s_add_u32 s28, s82, s17
	s_mov_b32 m0, s0
	v_readfirstlane_b32 s0, v9
	s_addc_u32 s29, s83, 0
	v_lshl_add_u64 v[4:5], v[4:5], 0, v[72:73]
	v_add_u32_e32 v8, 0x2000, v70
	s_mov_b32 m0, s0
	v_lshl_add_u64 v[6:7], s[28:29], 0, v[0:1]
	v_readfirstlane_b32 s0, v8
	v_add_u32_e32 v4, 0x3000, v70
	v_lshl_add_u64 v[2:3], s[28:29], 0, v[2:3]
	v_lshl_add_u64 v[6:7], v[6:7], 0, v[72:73]
	s_mov_b32 m0, s0
	v_readfirstlane_b32 s0, v4
	v_lshl_add_u64 v[2:3], v[2:3], 0, v[72:73]
	s_mov_b32 m0, s0
	v_lshrrev_b32_e32 v12, 2, v10
	v_lshrrev_b32_e32 v13, 3, v10
	v_xor_b32_e32 v2, v12, v13
	v_lshlrev_b32_e32 v2, 1, v2
	v_lshl_add_u64 v[0:1], s[8:9], 0, v[0:1]
	v_bfe_u32 v69, v10, 4, 2
	v_bfe_u32 v14, v10, 3, 1
	v_and_b32_e32 v2, 2, v2
	v_and_b32_e32 v75, 15, v10
	v_or_b32_e32 v0, v0, v72
	v_bfe_u32 v68, v10, 6, 1
	v_bitop3_b32 v2, v2, v69, v14 bitop3:0x36
	v_ashrrev_i32_e32 v74, 7, v10
	v_lshlrev_b32_e32 v3, 6, v75
	v_lshl_add_u64 v[66:67], s[82:83], 0, v[0:1]
	v_mov_b32_e32 v0, 0
	v_lshl_or_b32 v71, v2, 4, v3
	v_lshlrev_b32_e32 v77, 12, v74
	v_lshlrev_b32_e32 v78, 12, v68
	s_mov_b32 s8, 0
	s_mov_b64 s[0:1], 0
	v_mov_b32_e32 v1, v0
	v_mov_b32_e32 v2, v0
	v_mov_b32_e32 v3, v0
	v_mov_b32_e32 v4, v0
	v_mov_b32_e32 v5, v0
	v_mov_b32_e32 v6, v0
	v_mov_b32_e32 v7, v0
	v_mov_b32_e32 v8, v0
	v_mov_b32_e32 v9, v0
	v_mov_b32_e32 v10, v0
	v_mov_b32_e32 v11, v0
	v_mov_b32_e32 v12, v0
	v_mov_b32_e32 v13, v0
	v_mov_b32_e32 v14, v0
	v_mov_b32_e32 v15, v0
	v_mov_b32_e32 v16, v0
	v_mov_b32_e32 v17, v0
	v_mov_b32_e32 v18, v0
	v_mov_b32_e32 v19, v0
	s_waitcnt vmcnt(0)
	v_mov_b32_e32 v20, v0
	v_mov_b32_e32 v21, v0
	v_mov_b32_e32 v22, v0
	v_mov_b32_e32 v23, v0
	v_mov_b32_e32 v24, v0
	v_mov_b32_e32 v25, v0
	v_mov_b32_e32 v26, v0
	v_mov_b32_e32 v27, v0
	v_mov_b32_e32 v28, v0
	v_mov_b32_e32 v29, v0
	v_mov_b32_e32 v30, v0
	v_mov_b32_e32 v31, v0
	v_mov_b32_e32 v32, v0
	v_mov_b32_e32 v33, v0
	v_mov_b32_e32 v34, v0
	v_mov_b32_e32 v35, v0
	v_mov_b32_e32 v36, v0
	v_mov_b32_e32 v37, v0
	v_mov_b32_e32 v38, v0
	v_mov_b32_e32 v39, v0
	v_mov_b32_e32 v40, v0
	v_mov_b32_e32 v41, v0
	v_mov_b32_e32 v42, v0
	v_mov_b32_e32 v43, v0
	v_mov_b32_e32 v44, v0
	v_mov_b32_e32 v45, v0
	v_mov_b32_e32 v46, v0
	v_mov_b32_e32 v47, v0
	v_mov_b32_e32 v48, v0
	v_mov_b32_e32 v49, v0
	v_mov_b32_e32 v50, v0
	v_mov_b32_e32 v51, v0
	v_mov_b32_e32 v52, v0
	v_mov_b32_e32 v53, v0
	v_mov_b32_e32 v54, v0
	v_mov_b32_e32 v55, v0
	v_mov_b32_e32 v56, v0
	v_mov_b32_e32 v57, v0
	v_mov_b32_e32 v58, v0
	v_mov_b32_e32 v59, v0
	v_mov_b32_e32 v60, v0
	v_mov_b32_e32 v61, v0
	v_mov_b32_e32 v62, v0
	v_mov_b32_e32 v63, v0
	v_readlane_b32 s73, v165, 8
	v_readlane_b32 s74, v165, 9
	v_readlane_b32 s75, v165, 10
	v_readlane_b32 s76, v165, 11
	v_readlane_b32 s77, v165, 12
	v_readlane_b32 s78, v165, 13
	v_readlane_b32 s79, v165, 14
	v_readlane_b32 s80, v165, 15
	v_readlane_b32 s81, v165, 16
	v_readlane_b32 s84, v165, 19
	v_readlane_b32 s85, v165, 20
	v_readlane_b32 s86, v165, 21
	v_readlane_b32 s87, v165, 22
	v_and_b32_e32 v80, 15, v122
	v_bfe_u32 v81, v122, 4, 2
	v_bfe_u32 v82, v122, 1, 3
	v_xor_b32_e32 v81, v81, v82
	v_lshlrev_b32_e32 v81, 4, v81
	v_lshl_or_b32 v71, v80, 7, v81
	v_lshlrev_b32_e32 v77, 1, v77
	v_lshlrev_b32_e32 v78, 1, v78
	v_and_b32_e32 v80, 7, v122
	v_bfe_u32 v81, v122, 4, 3
	v_xor_b32_e32 v80, v80, v81
	v_lshlrev_b32_e32 v80, 4, v80
	v_lshrrev_b32_e32 v81, 3, v122
	v_lshl_or_b32 v80, v81, 11, v80
	v_bfe_u32 v81, v122, 4, 2
	v_lshrrev_b32_e32 v82, 1, v81
	v_xor_b32_e32 v83, v81, v82
	v_and_b32_e32 v83, 1, v83
	v_lshl_or_b32 v82, v83, 1, v82
	v_and_b32_e32 v81, 3, v122
	v_xor_b32_e32 v81, v81, v82
	v_lshlrev_b32_e32 v81, 4, v81
	v_lshrrev_b32_e32 v82, 2, v122
	v_lshl_or_b32 v81, v82, 11, v81
	v_sub_u32_e32 v80, v80, v81
	v_ashrrev_i32_e32 v81, 31, v80
	v_lshl_add_u64 v[64:65], v[64:65], 0, v[80:81]
	v_lshl_add_u64 v[66:67], v[66:67], 0, v[80:81]
	v_mov_b32_e32 v140, 0x10000
	v_mov_b32_e32 v141, 0

; DEV void phase_ml_in(const Params& p, unsigned char* smem) {
;     ...
;   for (int t = blockIdx.x; t < ntile; t += gridDim.x) {
;     int nt = t % 25, mt = t / 25;
;     const bf16_t* A = p.hbuf + (size_t)mt * 128 * 1024;
;     if (nt < 8 || (nt >= 16 && nt < 24)) {
;       bf16_t* obase = nt < 8 ? p.qb : p.ob - 2048;
.LBB0_845:
	s_and_b32 s0, s57, 7
	s_mul_i32 s1, s0, 0x19c
	s_min_u32 s0, s0, 4
	s_add_i32 s1, s1, s0
	s_lshr_b32 s0, s57, 3
	s_add_i32 s22, s1, s0
	s_mul_hi_i32 s0, s22, 0x51eb851f
	s_lshr_b32 s1, s0, 31
	s_ashr_i32 s0, s0, 3
	s_add_i32 s20, s0, s1
	s_mul_i32 s0, s20, 25
	s_ashr_i32 s21, s20, 31
	s_sub_i32 s22, s22, s0
	s_lshl_b64 s[0:1], s[20:21], 18
	s_add_u32 s30, s46, s0
	s_addc_u32 s31, s47, s1
	s_cmp_lt_i32 s22, 8
	s_cselect_b64 s[28:29], -1, 0
	s_cmp_gt_i32 s22, 7
	s_cselect_b64 s[0:1], -1, 0
	s_and_b32 s2, s22, 0x7ffffff8
	s_cmp_lg_u32 s2, 16
	s_cselect_b64 s[2:3], -1, 0
	s_and_b64 s[2:3], s[0:1], s[2:3]
	s_mov_b64 s[0:1], -1
	s_and_b64 vcc, exec, s[2:3]
	s_cbranch_vccnz .LBB0_847
	s_and_b64 vcc, exec, s[0:1]
	s_cbranch_vccz .LBB0_844
	s_branch .LBB0_1639

; DEV int otid() { int t = threadIdx.x; asm volatile("" : "+v"(t)); return t; }
; template <bool SWAP, class RowA, class Epi>
; DEV void gemm_tile(unsigned char* smem, RowA rowA, const bf16_t* Bt, int K, Epi epi) {
;   const int tid = otid(), lane = tid & 63, wid = tid >> 6, wr = wid >> 1, wc = wid & 1, fr = lane & 15, fq = lane >> 4;
;   const int r0 = tid >> 2;
;   const int a_w = (r0 >> 2) & 3, g_w = (((a_w ^ (a_w >> 1)) & 1) << 1) | (a_w >> 1);
;   const int cc = ((tid & 3) ^ g_w) * 8;
;   const int a_r = (fr >> 2) & 3, g_r = (((a_r ^ (a_r >> 1)) & 1) << 1) | (a_r >> 1);
;   const int rdoff = fr * 64 + ((fq ^ g_r) * 16);
;   const bf16_t* a0 = rowA(r0) + cc;
;   const bf16_t* a1 = rowA(r0 + 64) + cc;
;   const bf16_t* b0 = Bt + (size_t)r0 * K + cc;
;   const bf16_t* b1 = Bt + (size_t)(r0 + 64) * K + cc;
;   f32x4 acc[4][4];
; #pragma unroll
;   for (int m = 0; m < 4; ++m)
; #pragma unroll
;     for (int n = 0; n < 4; ++n) acc[m][n] = f32x4{0.f, 0.f, 0.f, 0.f};
; DEV void phase_proj_out(const Params& p, const bf16_t* Abuf, const bf16_t* Wt, const float* bias, int nrows, unsigned char* smem, bool drain) {
;     ...
;   for (int t = blockIdx.x; t < ntile; t += gridDim.x) {
;     int nt = t & 7, mt = t >> 3;
;     const bf16_t* A = Abuf + (size_t)mt * 128 * 1024;
;     gemm_tile<true>(smem, [&](int r) { return A + (size_t)r * 1024; }, Wt + (size_t)nt * 128 * 1024, 1024,
.LBB0_2055:
	v_mov_b32_e32 v10, v122
	s_and_b32 s0, s14, 7
	s_lshl_b32 s0, s0, 7
	s_lshr_b32 s10, s14, 3
	s_add_i32 s0, s0, s10
	s_and_b32 s15, s0, 7
	s_ashr_i32 s10, s0, 3
	v_lshrrev_b32_e32 v1, 4, v10
	v_lshrrev_b32_e32 v2, 5, v10
	v_readlane_b32 s48, v165, 39
	v_xor_b32_e32 v1, v1, v2
	s_mov_b32 s0, s15
	s_ashr_i32 s11, s10, 31
	v_readlane_b32 s52, v165, 43
	v_readlane_b32 s53, v165, 44
	v_lshlrev_b32_e32 v1, 1, v1
	s_lshl_b32 s0, s0, 18
	s_lshl_b64 s[12:13], s[10:11], 18
	v_readlane_b32 s54, v165, 45
	v_readlane_b32 s55, v165, 46
	v_readlane_b32 s56, v165, 47
	v_readlane_b32 s57, v165, 48
	v_readlane_b32 s58, v165, 49
	v_readlane_b32 s59, v165, 50
	v_readlane_b32 s60, v165, 51
	v_readlane_b32 s61, v165, 52
	v_readlane_b32 s62, v165, 53
	v_readlane_b32 s63, v165, 54
	s_mov_b64 s[16:17], s[52:53]
	v_ashrrev_i32_e32 v0, 2, v10
	v_bfe_u32 v3, v10, 5, 1
	v_and_b32_e32 v1, 2, v1
	v_and_b32_e32 v2, 3, v10
	v_readlane_b32 s49, v165, 40
	v_readlane_b32 s50, v165, 41
	v_readlane_b32 s51, v165, 42
	s_add_u32 s12, s16, s12
	v_bitop3_b32 v11, v1, v2, v3 bitop3:0x36
	v_ashrrev_i32_e32 v1, 31, v0
	s_mov_b64 s[18:19], s[54:55]
	s_mov_b64 s[20:21], s[56:57]
	s_mov_b64 s[22:23], s[58:59]
	s_mov_b64 s[24:25], s[60:61]
	s_mov_b64 s[26:27], s[62:63]
	s_addc_u32 s13, s17, s13
	v_readlane_b32 s48, v165, 7
	v_lshlrev_b64 v[0:1], 11, v[0:1]
	s_lshl_b32 s11, s15, 18
	v_readlane_b32 s62, v165, 21
	v_lshl_add_u64 v[8:9], s[12:13], 0, v[0:1]
	v_lshlrev_b32_e32 v64, 4, v11
	v_lshlrev_b32_e32 v74, 4, v10
	s_add_u32 s16, s62, s11
	v_lshl_add_u64 v[2:3], v[0:1], 0, s[4:5]
	v_lshl_add_u64 v[66:67], v[8:9], 0, v[64:65]
	v_readfirstlane_b32 s11, v74
	v_add_u32_e32 v9, 0x1000, v74
	v_readlane_b32 s63, v165, 22
	v_lshl_add_u64 v[4:5], s[12:13], 0, v[2:3]
	s_mov_b32 m0, s11
	v_readfirstlane_b32 s11, v9
	s_addc_u32 s17, s63, 0
	v_lshl_add_u64 v[4:5], v[4:5], 0, v[64:65]
	v_add_u32_e32 v8, 0x2000, v74
	s_mov_b32 m0, s11
	v_lshl_add_u64 v[6:7], s[16:17], 0, v[0:1]
	v_readfirstlane_b32 s11, v8
	v_add_u32_e32 v4, 0x3000, v74
	v_lshl_add_u64 v[2:3], s[16:17], 0, v[2:3]
	v_lshl_add_u64 v[6:7], v[6:7], 0, v[64:65]
	s_mov_b32 m0, s11
	v_readfirstlane_b32 s11, v4
	v_lshl_add_u64 v[2:3], v[2:3], 0, v[64:65]
	s_mov_b32 m0, s11
	v_lshrrev_b32_e32 v12, 2, v10
	v_lshrrev_b32_e32 v13, 3, v10
	v_xor_b32_e32 v2, v12, v13
	v_lshlrev_b32_e32 v2, 1, v2
	v_lshl_add_u64 v[0:1], s[0:1], 0, v[0:1]
	v_bfe_u32 v71, v10, 4, 2
	v_bfe_u32 v14, v10, 3, 1
	v_and_b32_e32 v2, 2, v2
	v_and_b32_e32 v73, 15, v10
	v_or_b32_e32 v0, v0, v64
	v_bfe_u32 v70, v10, 6, 1
	v_bitop3_b32 v2, v2, v71, v14 bitop3:0x36
	v_ashrrev_i32_e32 v72, 7, v10
	v_lshlrev_b32_e32 v3, 6, v73
	v_lshl_add_u64 v[68:69], s[62:63], 0, v[0:1]
	v_mov_b32_e32 v0, 0
	v_lshl_or_b32 v75, v2, 4, v3
	v_lshlrev_b32_e32 v76, 12, v72
	v_lshlrev_b32_e32 v77, 12, v70
	s_mov_b32 s0, 0
	s_mov_b64 s[12:13], 0
	v_mov_b32_e32 v1, v0
	v_mov_b32_e32 v2, v0
	v_mov_b32_e32 v3, v0
	v_mov_b32_e32 v4, v0
	v_mov_b32_e32 v5, v0
	v_mov_b32_e32 v6, v0
	v_mov_b32_e32 v7, v0
	v_mov_b32_e32 v8, v0
	v_mov_b32_e32 v9, v0
	v_mov_b32_e32 v10, v0
	v_mov_b32_e32 v11, v0
	v_mov_b32_e32 v12, v0
	v_mov_b32_e32 v13, v0
	v_mov_b32_e32 v14, v0
	v_mov_b32_e32 v15, v0
	v_mov_b32_e32 v16, v0
	v_mov_b32_e32 v17, v0
	v_mov_b32_e32 v18, v0
	v_mov_b32_e32 v19, v0
	v_mov_b32_e32 v20, v0
	v_mov_b32_e32 v21, v0
	v_mov_b32_e32 v22, v0
	v_mov_b32_e32 v23, v0
	v_mov_b32_e32 v24, v0
	v_mov_b32_e32 v25, v0
	v_mov_b32_e32 v26, v0
	v_mov_b32_e32 v27, v0
	v_mov_b32_e32 v28, v0
	v_mov_b32_e32 v29, v0
	v_mov_b32_e32 v30, v0
	v_mov_b32_e32 v31, v0
	v_mov_b32_e32 v32, v0
	v_mov_b32_e32 v33, v0
	v_mov_b32_e32 v34, v0
	v_mov_b32_e32 v35, v0
	v_mov_b32_e32 v36, v0
	v_mov_b32_e32 v37, v0
	v_mov_b32_e32 v38, v0
	v_mov_b32_e32 v39, v0
	v_mov_b32_e32 v40, v0
	v_mov_b32_e32 v41, v0
	v_mov_b32_e32 v42, v0
	v_mov_b32_e32 v43, v0
	v_mov_b32_e32 v44, v0
	v_mov_b32_e32 v45, v0
	v_mov_b32_e32 v46, v0
	v_mov_b32_e32 v47, v0
	v_mov_b32_e32 v48, v0
	v_mov_b32_e32 v49, v0
	v_mov_b32_e32 v50, v0
	v_mov_b32_e32 v51, v0
	v_mov_b32_e32 v52, v0
	v_mov_b32_e32 v53, v0
	v_mov_b32_e32 v54, v0
	v_mov_b32_e32 v55, v0
	v_mov_b32_e32 v56, v0
	v_mov_b32_e32 v57, v0
	v_mov_b32_e32 v58, v0
	v_mov_b32_e32 v59, v0
	v_mov_b32_e32 v60, v0
	v_mov_b32_e32 v61, v0
	v_mov_b32_e32 v62, v0
	v_mov_b32_e32 v63, v0
	v_readlane_b32 s49, v165, 8
	v_readlane_b32 s50, v165, 9
	v_readlane_b32 s51, v165, 10
	v_readlane_b32 s52, v165, 11
	v_readlane_b32 s53, v165, 12
	v_readlane_b32 s54, v165, 13
	v_readlane_b32 s55, v165, 14
	v_readlane_b32 s56, v165, 15
	v_readlane_b32 s57, v165, 16
	v_readlane_b32 s58, v165, 17
	v_readlane_b32 s59, v165, 18
	v_readlane_b32 s60, v165, 19
	v_readlane_b32 s61, v165, 20
	v_and_b32_e32 v78, 15, v122
	v_bfe_u32 v79, v122, 4, 2
	v_bfe_u32 v80, v122, 1, 3
	v_xor_b32_e32 v79, v79, v80
	v_lshlrev_b32_e32 v79, 4, v79
	v_lshl_or_b32 v75, v78, 7, v79
	v_lshlrev_b32_e32 v76, 1, v76
	v_lshlrev_b32_e32 v77, 1, v77
	v_and_b32_e32 v78, 7, v122
	v_bfe_u32 v79, v122, 4, 3
	v_xor_b32_e32 v78, v78, v79
	v_lshlrev_b32_e32 v78, 4, v78
	v_lshrrev_b32_e32 v79, 3, v122
	v_lshl_or_b32 v78, v79, 11, v78
	v_bfe_u32 v79, v122, 4, 2
	v_lshrrev_b32_e32 v80, 1, v79
	v_xor_b32_e32 v81, v79, v80
	v_and_b32_e32 v81, 1, v81
	v_lshl_or_b32 v80, v81, 1, v80
	v_and_b32_e32 v79, 3, v122
	v_xor_b32_e32 v79, v79, v80
	v_lshlrev_b32_e32 v79, 4, v79
	v_lshrrev_b32_e32 v80, 2, v122
	v_lshl_or_b32 v79, v80, 11, v79
	v_sub_u32_e32 v78, v78, v79
	v_ashrrev_i32_e32 v79, 31, v78
	v_lshl_add_u64 v[66:67], v[66:67], 0, v[78:79]
	v_lshl_add_u64 v[68:69], v[68:69], 0, v[78:79]
	v_mov_b32_e32 v140, 0x10000
	v_mov_b32_e32 v141, 0
